# MLA up-projections: per-row sum of squares produced once in the w_in epilogue (scratch at the free yc region) instead of re-reading the A tile in every up-projection tile
# speedup vs baseline: 1.0146x; 1.0127x over previous
.LBB0_566:
	s_and_b64 vcc, exec, s[0:1]
	s_cbranch_vccz .LBB0_586
	s_add_i32 s0, s56, 0xfce8
	s_and_b32 s1, s0, 0xffff
	s_mul_i32 s1, s1, 0xf83f
	s_lshr_b32 s8, s1, 23
	s_mul_i32 s1, s8, 0x84
	s_sub_i32 s31, s0, s1
	s_waitcnt vmcnt(0)
	v_mov_b32_e32 v70, v163
	s_mov_b64 s[0:1], 0
	s_add_u32 s0, s26, s0
	v_and_b32_e32 v5, 31, v70
	s_addc_u32 s1, s27, s1
	s_lshl_b32 s31, s31, 7
	v_bfe_u32 v4, v70, 5, 1
	v_ashrrev_i32_e32 v6, 2, v70
	v_lshlrev_b32_e32 v0, 4, v5
	s_mov_b64 s[40:41], 0
	s_and_b32 s31, s31, 0xff80
	v_lshl_add_u64 v[2:3], s[0:1], 0, v[0:1]
	v_cmp_eq_u32_e32 vcc, 0, v5
	v_lshrrev_b32_e32 v5, 4, v6
	v_lshlrev_b32_e32 v0, 2, v4
	s_mov_b64 s[0:1], 0x1e00
	v_lshl_or_b32 v0, v5, 7, v0
	v_lshl_add_u32 v5, v5, 5, s31
	s_mov_b64 s[40:41], 0
	s_mov_b64 s[42:43], 0
	v_lshl_add_u64 v[2:3], v[2:3], 0, s[0:1]
	v_or3_b32 v4, v5, v4, 6
	s_movk_i32 s39, 0xff80
	v_and_b32_e32 v5, 31, v70
	v_bfe_u32 v6, v70, 5, 1
	v_add_u32_e32 v7, -6, v4
	v_sub_u32_e32 v7, v7, v6
	v_add_u32_e32 v7, v7, v5
	v_lshlrev_b32_e32 v7, 2, v7
	s_add_u32 s0, s26, 0x16c22000
	s_addc_u32 s1, s27, 0
	s_add_u32 s42, s0, 0x11000
	s_addc_u32 s43, s1, 0
	global_load_dword v8, v7, s[0:1]
	global_load_dword v9, v7, s[42:43]
	v_lshlrev_b32_e32 v6, 2, v6
	v_sub_u32_e32 v10, v0, v6
	v_lshl_add_u32 v10, v5, 2, v10
	v_add_u32_e32 v10, 0x10000, v10
	s_waitcnt vmcnt(0)
	v_add_f32_e32 v6, v8, v9
	s_nop 0
	v_fmamk_f32 v6, v6, 0x3b800000, v162
	v_mul_f32_e32 v7, 0x4b800000, v6
	v_cmp_gt_f32_e64 s[0:1], s78, v6
	s_nop 1
	v_cndmask_b32_e64 v6, v6, v7, s[0:1]
	v_rsq_f32_e32 v6, v6
	s_nop 0
	v_mul_f32_e32 v7, 0x45800000, v6
	v_cndmask_b32_e64 v6, v6, v7, s[0:1]
	ds_write_b32 v10, v6
	v_add_u32_e32 v4, 32, v4
	s_mov_b32 s39, 0
	s_mov_b64 s[42:43], 0

.LBB0_587:
	s_andn2_b64 vcc, exec, s[0:1]
	s_cbranch_vccnz .LBB0_554
	s_mul_hi_i32 s0, s56, 0x3e0f83e1
	s_lshr_b32 s1, s0, 31
	s_ashr_i32 s8, s0, 5
	s_add_i32 s8, s8, s1
	s_waitcnt vmcnt(0)
	v_mov_b32_e32 v70, v163
	s_mov_b64 s[0:1], 0
	s_add_u32 s0, s26, s0
	v_and_b32_e32 v5, 31, v70
	s_addc_u32 s1, s27, s1
	v_bfe_u32 v4, v70, 5, 1
	v_ashrrev_i32_e32 v6, 2, v70
	v_lshlrev_b32_e32 v0, 4, v5
	v_lshl_add_u64 v[2:3], s[0:1], 0, v[0:1]
	v_cmp_eq_u32_e32 vcc, 0, v5
	v_lshrrev_b32_e32 v5, 4, v6
	v_lshlrev_b32_e32 v0, 2, v4
	v_lshl_or_b32 v4, s56, 7, v4
	s_mov_b64 s[40:41], 0
	s_mov_b64 s[0:1], 0x1c00
	v_lshl_add_u32 v4, v5, 5, v4
	v_lshl_add_u64 v[2:3], v[2:3], 0, s[0:1]
	v_or_b32_e32 v4, 6, v4
	s_mul_i32 s0, s8, 0x4200
	v_and_b32_e32 v71, 63, v70
	s_mov_b64 s[40:41], 0
	s_mov_b64 s[44:45], 0
	v_lshl_or_b32 v0, v5, 7, v0
	v_subrev_u32_e32 v4, s0, v4
	s_movk_i32 s31, 0xff80
	v_and_b32_e32 v5, 31, v70
	v_bfe_u32 v6, v70, 5, 1
	v_add_u32_e32 v7, -6, v4
	v_sub_u32_e32 v7, v7, v6
	v_add_u32_e32 v7, v7, v5
	v_lshlrev_b32_e32 v7, 2, v7
	s_add_u32 s0, s26, 0x16c00000
	s_addc_u32 s1, s27, 0
	s_add_u32 s42, s0, 0x11000
	s_addc_u32 s43, s1, 0
	global_load_dword v8, v7, s[0:1]
	global_load_dword v9, v7, s[42:43]
	v_lshlrev_b32_e32 v6, 2, v6
	v_sub_u32_e32 v10, v0, v6
	v_lshl_add_u32 v10, v5, 2, v10
	v_add_u32_e32 v10, 0x10000, v10
	s_waitcnt vmcnt(0)
	v_add_f32_e32 v6, v8, v9
	s_nop 0
	v_fmamk_f32 v6, v6, 0x3b800000, v162
	v_mul_f32_e32 v7, 0x4b800000, v6
	v_cmp_gt_f32_e64 s[0:1], s78, v6
	s_nop 1
	v_cndmask_b32_e64 v6, v6, v7, s[0:1]
	v_rsq_f32_e32 v6, v6
	s_nop 0
	v_mul_f32_e32 v7, 0x45800000, v6
	v_cndmask_b32_e64 v6, v6, v7, s[0:1]
	ds_write_b32 v10, v6
	v_add_u32_e32 v4, 32, v4
	s_mov_b32 s31, 0
	s_mov_b64 s[42:43], 0

.Lg2_win_episel:
	s_cmp_lt_u32 s38, 4
	s_cbranch_scc1 .Lg2_win_epiR_pre
	s_sub_u32 s0, s38, 16
	s_cmp_lt_u32 s0, 4
	s_cbranch_scc1 .Lg2_win_epiS
	s_sub_u32 s0, s38, 28
	s_cmp_lt_u32 s0, 4
	s_cbranch_scc1 .Lg2_win_epiQ
	s_branch .Lg2_win_epiP

.Lg2_win_epiQ:
	s_nop 7
	s_nop 7
	s_barrier
	v_cvt_pk_bf16_f32 v0, v0, v1
	v_cvt_pk_bf16_f32 v1, v2, v3
	ds_write_b64 v212, v[0:1] offset:0
	v_lshlrev_b32_e32 v164, 16, v0
	v_and_b32_e32 v165, 0xffff0000, v0
	v_lshlrev_b32_e32 v166, 16, v1
	v_and_b32_e32 v167, 0xffff0000, v1
	v_mul_f32_e32 v136, v164, v164
	v_fmac_f32_e32 v136, v165, v165
	v_fmac_f32_e32 v136, v166, v166
	v_fmac_f32_e32 v136, v167, v167
	v_cvt_pk_bf16_f32 v4, v4, v5
	v_cvt_pk_bf16_f32 v5, v6, v7
	ds_write_b64 v213, v[4:5] offset:0
	v_lshlrev_b32_e32 v164, 16, v4
	v_and_b32_e32 v165, 0xffff0000, v4
	v_lshlrev_b32_e32 v166, 16, v5
	v_and_b32_e32 v167, 0xffff0000, v5
	v_fmac_f32_e32 v136, v164, v164
	v_fmac_f32_e32 v136, v165, v165
	v_fmac_f32_e32 v136, v166, v166
	v_fmac_f32_e32 v136, v167, v167
	v_cvt_pk_bf16_f32 v8, v8, v9
	v_cvt_pk_bf16_f32 v9, v10, v11
	ds_write_b64 v212, v[8:9] offset:4096
	v_lshlrev_b32_e32 v164, 16, v8
	v_and_b32_e32 v165, 0xffff0000, v8
	v_lshlrev_b32_e32 v166, 16, v9
	v_and_b32_e32 v167, 0xffff0000, v9
	v_mul_f32_e32 v137, v164, v164
	v_fmac_f32_e32 v137, v165, v165
	v_fmac_f32_e32 v137, v166, v166
	v_fmac_f32_e32 v137, v167, v167
	v_cvt_pk_bf16_f32 v12, v12, v13
	v_cvt_pk_bf16_f32 v13, v14, v15
	ds_write_b64 v213, v[12:13] offset:4096
	v_lshlrev_b32_e32 v164, 16, v12
	v_and_b32_e32 v165, 0xffff0000, v12
	v_lshlrev_b32_e32 v166, 16, v13
	v_and_b32_e32 v167, 0xffff0000, v13
	v_fmac_f32_e32 v137, v164, v164
	v_fmac_f32_e32 v137, v165, v165
	v_fmac_f32_e32 v137, v166, v166
	v_fmac_f32_e32 v137, v167, v167
	v_cvt_pk_bf16_f32 v16, v16, v17
	v_cvt_pk_bf16_f32 v17, v18, v19
	ds_write_b64 v212, v[16:17] offset:8192
	v_lshlrev_b32_e32 v164, 16, v16
	v_and_b32_e32 v165, 0xffff0000, v16
	v_lshlrev_b32_e32 v166, 16, v17
	v_and_b32_e32 v167, 0xffff0000, v17
	v_mul_f32_e32 v138, v164, v164
	v_fmac_f32_e32 v138, v165, v165
	v_fmac_f32_e32 v138, v166, v166
	v_fmac_f32_e32 v138, v167, v167
	v_cvt_pk_bf16_f32 v20, v20, v21
	v_cvt_pk_bf16_f32 v21, v22, v23
	ds_write_b64 v213, v[20:21] offset:8192
	v_lshlrev_b32_e32 v164, 16, v20
	v_and_b32_e32 v165, 0xffff0000, v20
	v_lshlrev_b32_e32 v166, 16, v21
	v_and_b32_e32 v167, 0xffff0000, v21
	v_fmac_f32_e32 v138, v164, v164
	v_fmac_f32_e32 v138, v165, v165
	v_fmac_f32_e32 v138, v166, v166
	v_fmac_f32_e32 v138, v167, v167
	v_cvt_pk_bf16_f32 v24, v24, v25
	v_cvt_pk_bf16_f32 v25, v26, v27
	ds_write_b64 v212, v[24:25] offset:12288
	v_lshlrev_b32_e32 v164, 16, v24
	v_and_b32_e32 v165, 0xffff0000, v24
	v_lshlrev_b32_e32 v166, 16, v25
	v_and_b32_e32 v167, 0xffff0000, v25
	v_mul_f32_e32 v139, v164, v164
	v_fmac_f32_e32 v139, v165, v165
	v_fmac_f32_e32 v139, v166, v166
	v_fmac_f32_e32 v139, v167, v167
	v_cvt_pk_bf16_f32 v28, v28, v29
	v_cvt_pk_bf16_f32 v29, v30, v31
	ds_write_b64 v213, v[28:29] offset:12288
	v_lshlrev_b32_e32 v164, 16, v28
	v_and_b32_e32 v165, 0xffff0000, v28
	v_lshlrev_b32_e32 v166, 16, v29
	v_and_b32_e32 v167, 0xffff0000, v29
	v_fmac_f32_e32 v139, v164, v164
	v_fmac_f32_e32 v139, v165, v165
	v_fmac_f32_e32 v139, v166, v166
	v_fmac_f32_e32 v139, v167, v167
	v_cvt_pk_bf16_f32 v32, v32, v33
	v_cvt_pk_bf16_f32 v33, v34, v35
	ds_write_b64 v212, v[32:33] offset:16384
	v_lshlrev_b32_e32 v164, 16, v32
	v_and_b32_e32 v165, 0xffff0000, v32
	v_lshlrev_b32_e32 v166, 16, v33
	v_and_b32_e32 v167, 0xffff0000, v33
	v_mul_f32_e32 v140, v164, v164
	v_fmac_f32_e32 v140, v165, v165
	v_fmac_f32_e32 v140, v166, v166
	v_fmac_f32_e32 v140, v167, v167
	v_cvt_pk_bf16_f32 v36, v36, v37
	v_cvt_pk_bf16_f32 v37, v38, v39
	ds_write_b64 v213, v[36:37] offset:16384
	v_lshlrev_b32_e32 v164, 16, v36
	v_and_b32_e32 v165, 0xffff0000, v36
	v_lshlrev_b32_e32 v166, 16, v37
	v_and_b32_e32 v167, 0xffff0000, v37
	v_fmac_f32_e32 v140, v164, v164
	v_fmac_f32_e32 v140, v165, v165
	v_fmac_f32_e32 v140, v166, v166
	v_fmac_f32_e32 v140, v167, v167
	v_cvt_pk_bf16_f32 v40, v40, v41
	v_cvt_pk_bf16_f32 v41, v42, v43
	ds_write_b64 v212, v[40:41] offset:20480
	v_lshlrev_b32_e32 v164, 16, v40
	v_and_b32_e32 v165, 0xffff0000, v40
	v_lshlrev_b32_e32 v166, 16, v41
	v_and_b32_e32 v167, 0xffff0000, v41
	v_mul_f32_e32 v141, v164, v164
	v_fmac_f32_e32 v141, v165, v165
	v_fmac_f32_e32 v141, v166, v166
	v_fmac_f32_e32 v141, v167, v167
	v_cvt_pk_bf16_f32 v44, v44, v45
	v_cvt_pk_bf16_f32 v45, v46, v47
	ds_write_b64 v213, v[44:45] offset:20480
	v_lshlrev_b32_e32 v164, 16, v44
	v_and_b32_e32 v165, 0xffff0000, v44
	v_lshlrev_b32_e32 v166, 16, v45
	v_and_b32_e32 v167, 0xffff0000, v45
	v_fmac_f32_e32 v141, v164, v164
	v_fmac_f32_e32 v141, v165, v165
	v_fmac_f32_e32 v141, v166, v166
	v_fmac_f32_e32 v141, v167, v167
	v_cvt_pk_bf16_f32 v48, v48, v49
	v_cvt_pk_bf16_f32 v49, v50, v51
	ds_write_b64 v212, v[48:49] offset:24576
	v_lshlrev_b32_e32 v164, 16, v48
	v_and_b32_e32 v165, 0xffff0000, v48
	v_lshlrev_b32_e32 v166, 16, v49
	v_and_b32_e32 v167, 0xffff0000, v49
	v_mul_f32_e32 v142, v164, v164
	v_fmac_f32_e32 v142, v165, v165
	v_fmac_f32_e32 v142, v166, v166
	v_fmac_f32_e32 v142, v167, v167
	v_cvt_pk_bf16_f32 v52, v52, v53
	v_cvt_pk_bf16_f32 v53, v54, v55
	ds_write_b64 v213, v[52:53] offset:24576
	v_lshlrev_b32_e32 v164, 16, v52
	v_and_b32_e32 v165, 0xffff0000, v52
	v_lshlrev_b32_e32 v166, 16, v53
	v_and_b32_e32 v167, 0xffff0000, v53
	v_fmac_f32_e32 v142, v164, v164
	v_fmac_f32_e32 v142, v165, v165
	v_fmac_f32_e32 v142, v166, v166
	v_fmac_f32_e32 v142, v167, v167
	v_cvt_pk_bf16_f32 v56, v56, v57
	v_cvt_pk_bf16_f32 v57, v58, v59
	ds_write_b64 v212, v[56:57] offset:28672
	v_lshlrev_b32_e32 v164, 16, v56
	v_and_b32_e32 v165, 0xffff0000, v56
	v_lshlrev_b32_e32 v166, 16, v57
	v_and_b32_e32 v167, 0xffff0000, v57
	v_mul_f32_e32 v143, v164, v164
	v_fmac_f32_e32 v143, v165, v165
	v_fmac_f32_e32 v143, v166, v166
	v_fmac_f32_e32 v143, v167, v167
	v_cvt_pk_bf16_f32 v60, v60, v61
	v_cvt_pk_bf16_f32 v61, v62, v63
	ds_write_b64 v213, v[60:61] offset:28672
	v_lshlrev_b32_e32 v164, 16, v60
	v_and_b32_e32 v165, 0xffff0000, v60
	v_lshlrev_b32_e32 v166, 16, v61
	v_and_b32_e32 v167, 0xffff0000, v61
	v_fmac_f32_e32 v143, v164, v164
	v_fmac_f32_e32 v143, v165, v165
	v_fmac_f32_e32 v143, v166, v166
	v_fmac_f32_e32 v143, v167, v167
	v_cvt_pk_bf16_f32 v64, v64, v65
	v_cvt_pk_bf16_f32 v65, v66, v67
	ds_write_b64 v253, v[64:65] offset:0
	v_lshlrev_b32_e32 v164, 16, v64
	v_and_b32_e32 v165, 0xffff0000, v64
	v_lshlrev_b32_e32 v166, 16, v65
	v_and_b32_e32 v167, 0xffff0000, v65
	v_mul_f32_e32 v144, v164, v164
	v_fmac_f32_e32 v144, v165, v165
	v_fmac_f32_e32 v144, v166, v166
	v_fmac_f32_e32 v144, v167, v167
	v_cvt_pk_bf16_f32 v68, v68, v69
	v_cvt_pk_bf16_f32 v69, v70, v71
	ds_write_b64 v254, v[68:69] offset:0
	v_lshlrev_b32_e32 v164, 16, v68
	v_and_b32_e32 v165, 0xffff0000, v68
	v_lshlrev_b32_e32 v166, 16, v69
	v_and_b32_e32 v167, 0xffff0000, v69
	v_fmac_f32_e32 v144, v164, v164
	v_fmac_f32_e32 v144, v165, v165
	v_fmac_f32_e32 v144, v166, v166
	v_fmac_f32_e32 v144, v167, v167
	v_cvt_pk_bf16_f32 v72, v72, v73
	v_cvt_pk_bf16_f32 v73, v74, v75
	ds_write_b64 v253, v[72:73] offset:4096
	v_lshlrev_b32_e32 v164, 16, v72
	v_and_b32_e32 v165, 0xffff0000, v72
	v_lshlrev_b32_e32 v166, 16, v73
	v_and_b32_e32 v167, 0xffff0000, v73
	v_mul_f32_e32 v145, v164, v164
	v_fmac_f32_e32 v145, v165, v165
	v_fmac_f32_e32 v145, v166, v166
	v_fmac_f32_e32 v145, v167, v167
	v_cvt_pk_bf16_f32 v76, v76, v77
	v_cvt_pk_bf16_f32 v77, v78, v79
	ds_write_b64 v254, v[76:77] offset:4096
	v_lshlrev_b32_e32 v164, 16, v76
	v_and_b32_e32 v165, 0xffff0000, v76
	v_lshlrev_b32_e32 v166, 16, v77
	v_and_b32_e32 v167, 0xffff0000, v77
	v_fmac_f32_e32 v145, v164, v164
	v_fmac_f32_e32 v145, v165, v165
	v_fmac_f32_e32 v145, v166, v166
	v_fmac_f32_e32 v145, v167, v167
	v_cvt_pk_bf16_f32 v80, v80, v81
	v_cvt_pk_bf16_f32 v81, v82, v83
	ds_write_b64 v253, v[80:81] offset:8192
	v_lshlrev_b32_e32 v164, 16, v80
	v_and_b32_e32 v165, 0xffff0000, v80
	v_lshlrev_b32_e32 v166, 16, v81
	v_and_b32_e32 v167, 0xffff0000, v81
	v_mul_f32_e32 v146, v164, v164
	v_fmac_f32_e32 v146, v165, v165
	v_fmac_f32_e32 v146, v166, v166
	v_fmac_f32_e32 v146, v167, v167
	v_cvt_pk_bf16_f32 v84, v84, v85
	v_cvt_pk_bf16_f32 v85, v86, v87
	ds_write_b64 v254, v[84:85] offset:8192
	v_lshlrev_b32_e32 v164, 16, v84
	v_and_b32_e32 v165, 0xffff0000, v84
	v_lshlrev_b32_e32 v166, 16, v85
	v_and_b32_e32 v167, 0xffff0000, v85
	v_fmac_f32_e32 v146, v164, v164
	v_fmac_f32_e32 v146, v165, v165
	v_fmac_f32_e32 v146, v166, v166
	v_fmac_f32_e32 v146, v167, v167
	v_cvt_pk_bf16_f32 v88, v88, v89
	v_cvt_pk_bf16_f32 v89, v90, v91
	ds_write_b64 v253, v[88:89] offset:12288
	v_lshlrev_b32_e32 v164, 16, v88
	v_and_b32_e32 v165, 0xffff0000, v88
	v_lshlrev_b32_e32 v166, 16, v89
	v_and_b32_e32 v167, 0xffff0000, v89
	v_mul_f32_e32 v147, v164, v164
	v_fmac_f32_e32 v147, v165, v165
	v_fmac_f32_e32 v147, v166, v166
	v_fmac_f32_e32 v147, v167, v167
	v_cvt_pk_bf16_f32 v92, v92, v93
	v_cvt_pk_bf16_f32 v93, v94, v95
	ds_write_b64 v254, v[92:93] offset:12288
	v_lshlrev_b32_e32 v164, 16, v92
	v_and_b32_e32 v165, 0xffff0000, v92
	v_lshlrev_b32_e32 v166, 16, v93
	v_and_b32_e32 v167, 0xffff0000, v93
	v_fmac_f32_e32 v147, v164, v164
	v_fmac_f32_e32 v147, v165, v165
	v_fmac_f32_e32 v147, v166, v166
	v_fmac_f32_e32 v147, v167, v167
	v_cvt_pk_bf16_f32 v96, v96, v97
	v_cvt_pk_bf16_f32 v97, v98, v99
	ds_write_b64 v253, v[96:97] offset:16384
	v_lshlrev_b32_e32 v164, 16, v96
	v_and_b32_e32 v165, 0xffff0000, v96
	v_lshlrev_b32_e32 v166, 16, v97
	v_and_b32_e32 v167, 0xffff0000, v97
	v_mul_f32_e32 v148, v164, v164
	v_fmac_f32_e32 v148, v165, v165
	v_fmac_f32_e32 v148, v166, v166
	v_fmac_f32_e32 v148, v167, v167
	v_cvt_pk_bf16_f32 v100, v100, v101
	v_cvt_pk_bf16_f32 v101, v102, v103
	ds_write_b64 v254, v[100:101] offset:16384
	v_lshlrev_b32_e32 v164, 16, v100
	v_and_b32_e32 v165, 0xffff0000, v100
	v_lshlrev_b32_e32 v166, 16, v101
	v_and_b32_e32 v167, 0xffff0000, v101
	v_fmac_f32_e32 v148, v164, v164
	v_fmac_f32_e32 v148, v165, v165
	v_fmac_f32_e32 v148, v166, v166
	v_fmac_f32_e32 v148, v167, v167
	v_cvt_pk_bf16_f32 v104, v104, v105
	v_cvt_pk_bf16_f32 v105, v106, v107
	ds_write_b64 v253, v[104:105] offset:20480
	v_lshlrev_b32_e32 v164, 16, v104
	v_and_b32_e32 v165, 0xffff0000, v104
	v_lshlrev_b32_e32 v166, 16, v105
	v_and_b32_e32 v167, 0xffff0000, v105
	v_mul_f32_e32 v149, v164, v164
	v_fmac_f32_e32 v149, v165, v165
	v_fmac_f32_e32 v149, v166, v166
	v_fmac_f32_e32 v149, v167, v167
	v_cvt_pk_bf16_f32 v108, v108, v109
	v_cvt_pk_bf16_f32 v109, v110, v111
	ds_write_b64 v254, v[108:109] offset:20480
	v_lshlrev_b32_e32 v164, 16, v108
	v_and_b32_e32 v165, 0xffff0000, v108
	v_lshlrev_b32_e32 v166, 16, v109
	v_and_b32_e32 v167, 0xffff0000, v109
	v_fmac_f32_e32 v149, v164, v164
	v_fmac_f32_e32 v149, v165, v165
	v_fmac_f32_e32 v149, v166, v166
	v_fmac_f32_e32 v149, v167, v167
	v_cvt_pk_bf16_f32 v112, v112, v113
	v_cvt_pk_bf16_f32 v113, v114, v115
	ds_write_b64 v253, v[112:113] offset:24576
	v_lshlrev_b32_e32 v164, 16, v112
	v_and_b32_e32 v165, 0xffff0000, v112
	v_lshlrev_b32_e32 v166, 16, v113
	v_and_b32_e32 v167, 0xffff0000, v113
	v_mul_f32_e32 v150, v164, v164
	v_fmac_f32_e32 v150, v165, v165
	v_fmac_f32_e32 v150, v166, v166
	v_fmac_f32_e32 v150, v167, v167
	v_cvt_pk_bf16_f32 v116, v116, v117
	v_cvt_pk_bf16_f32 v117, v118, v119
	ds_write_b64 v254, v[116:117] offset:24576
	v_lshlrev_b32_e32 v164, 16, v116
	v_and_b32_e32 v165, 0xffff0000, v116
	v_lshlrev_b32_e32 v166, 16, v117
	v_and_b32_e32 v167, 0xffff0000, v117
	v_fmac_f32_e32 v150, v164, v164
	v_fmac_f32_e32 v150, v165, v165
	v_fmac_f32_e32 v150, v166, v166
	v_fmac_f32_e32 v150, v167, v167
	v_cvt_pk_bf16_f32 v120, v120, v121
	v_cvt_pk_bf16_f32 v121, v122, v123
	ds_write_b64 v253, v[120:121] offset:28672
	v_lshlrev_b32_e32 v164, 16, v120
	v_and_b32_e32 v165, 0xffff0000, v120
	v_lshlrev_b32_e32 v166, 16, v121
	v_and_b32_e32 v167, 0xffff0000, v121
	v_mul_f32_e32 v151, v164, v164
	v_fmac_f32_e32 v151, v165, v165
	v_fmac_f32_e32 v151, v166, v166
	v_fmac_f32_e32 v151, v167, v167
	v_cvt_pk_bf16_f32 v124, v124, v125
	v_cvt_pk_bf16_f32 v125, v126, v127
	ds_write_b64 v254, v[124:125] offset:28672
	v_lshlrev_b32_e32 v164, 16, v124
	v_and_b32_e32 v165, 0xffff0000, v124
	v_lshlrev_b32_e32 v166, 16, v125
	v_and_b32_e32 v167, 0xffff0000, v125
	v_fmac_f32_e32 v151, v164, v164
	v_fmac_f32_e32 v151, v165, v165
	v_fmac_f32_e32 v151, v166, v166
	v_fmac_f32_e32 v151, v167, v167
	s_cmp_eq_u32 s65, 0
	s_cbranch_scc1 .Lg2_win_st_lastQ
	v_cvt_pk_bf16_f32 v128, v128, v129
	v_cvt_pk_bf16_f32 v129, v130, v131
	ds_write_b64 v253, v[128:129] offset:32768
	v_lshlrev_b32_e32 v164, 16, v128
	v_and_b32_e32 v165, 0xffff0000, v128
	v_lshlrev_b32_e32 v166, 16, v129
	v_and_b32_e32 v167, 0xffff0000, v129
	v_mul_f32_e32 v152, v164, v164
	v_fmac_f32_e32 v152, v165, v165
	v_fmac_f32_e32 v152, v166, v166
	v_fmac_f32_e32 v152, v167, v167
	v_cvt_pk_bf16_f32 v132, v132, v133
	v_cvt_pk_bf16_f32 v133, v134, v135
	ds_write_b64 v254, v[132:133] offset:32768
	v_lshlrev_b32_e32 v164, 16, v132
	v_and_b32_e32 v165, 0xffff0000, v132
	v_lshlrev_b32_e32 v166, 16, v133
	v_and_b32_e32 v167, 0xffff0000, v133
	v_fmac_f32_e32 v152, v164, v164
	v_fmac_f32_e32 v152, v165, v165
	v_fmac_f32_e32 v152, v166, v166
	v_fmac_f32_e32 v152, v167, v167
.Lg2_win_st_lastQ:
	v_mov_b32_e32 v164, v136
	s_nop 1
	v_permlane16_swap_b32_e32 v136, v164
	v_add_f32_e32 v136, v136, v164
	v_mov_b32_e32 v164, v136
	s_nop 1
	v_permlane32_swap_b32_e32 v136, v164
	v_add_f32_e32 v136, v136, v164
	v_mov_b32_e32 v164, v137
	s_nop 1
	v_permlane16_swap_b32_e32 v137, v164
	v_add_f32_e32 v137, v137, v164
	v_mov_b32_e32 v164, v137
	s_nop 1
	v_permlane32_swap_b32_e32 v137, v164
	v_add_f32_e32 v137, v137, v164
	v_mov_b32_e32 v164, v138
	s_nop 1
	v_permlane16_swap_b32_e32 v138, v164
	v_add_f32_e32 v138, v138, v164
	v_mov_b32_e32 v164, v138
	s_nop 1
	v_permlane32_swap_b32_e32 v138, v164
	v_add_f32_e32 v138, v138, v164
	v_mov_b32_e32 v164, v139
	s_nop 1
	v_permlane16_swap_b32_e32 v139, v164
	v_add_f32_e32 v139, v139, v164
	v_mov_b32_e32 v164, v139
	s_nop 1
	v_permlane32_swap_b32_e32 v139, v164
	v_add_f32_e32 v139, v139, v164
	v_mov_b32_e32 v164, v140
	s_nop 1
	v_permlane16_swap_b32_e32 v140, v164
	v_add_f32_e32 v140, v140, v164
	v_mov_b32_e32 v164, v140
	s_nop 1
	v_permlane32_swap_b32_e32 v140, v164
	v_add_f32_e32 v140, v140, v164
	v_mov_b32_e32 v164, v141
	s_nop 1
	v_permlane16_swap_b32_e32 v141, v164
	v_add_f32_e32 v141, v141, v164
	v_mov_b32_e32 v164, v141
	s_nop 1
	v_permlane32_swap_b32_e32 v141, v164
	v_add_f32_e32 v141, v141, v164
	v_mov_b32_e32 v164, v142
	s_nop 1
	v_permlane16_swap_b32_e32 v142, v164
	v_add_f32_e32 v142, v142, v164
	v_mov_b32_e32 v164, v142
	s_nop 1
	v_permlane32_swap_b32_e32 v142, v164
	v_add_f32_e32 v142, v142, v164
	v_mov_b32_e32 v164, v143
	s_nop 1
	v_permlane16_swap_b32_e32 v143, v164
	v_add_f32_e32 v143, v143, v164
	v_mov_b32_e32 v164, v143
	s_nop 1
	v_permlane32_swap_b32_e32 v143, v164
	v_add_f32_e32 v143, v143, v164
	v_mov_b32_e32 v164, v144
	s_nop 1
	v_permlane16_swap_b32_e32 v144, v164
	v_add_f32_e32 v144, v144, v164
	v_mov_b32_e32 v164, v144
	s_nop 1
	v_permlane32_swap_b32_e32 v144, v164
	v_add_f32_e32 v144, v144, v164
	v_mov_b32_e32 v164, v145
	s_nop 1
	v_permlane16_swap_b32_e32 v145, v164
	v_add_f32_e32 v145, v145, v164
	v_mov_b32_e32 v164, v145
	s_nop 1
	v_permlane32_swap_b32_e32 v145, v164
	v_add_f32_e32 v145, v145, v164
	v_mov_b32_e32 v164, v146
	s_nop 1
	v_permlane16_swap_b32_e32 v146, v164
	v_add_f32_e32 v146, v146, v164
	v_mov_b32_e32 v164, v146
	s_nop 1
	v_permlane32_swap_b32_e32 v146, v164
	v_add_f32_e32 v146, v146, v164
	v_mov_b32_e32 v164, v147
	s_nop 1
	v_permlane16_swap_b32_e32 v147, v164
	v_add_f32_e32 v147, v147, v164
	v_mov_b32_e32 v164, v147
	s_nop 1
	v_permlane32_swap_b32_e32 v147, v164
	v_add_f32_e32 v147, v147, v164
	v_mov_b32_e32 v164, v148
	s_nop 1
	v_permlane16_swap_b32_e32 v148, v164
	v_add_f32_e32 v148, v148, v164
	v_mov_b32_e32 v164, v148
	s_nop 1
	v_permlane32_swap_b32_e32 v148, v164
	v_add_f32_e32 v148, v148, v164
	v_mov_b32_e32 v164, v149
	s_nop 1
	v_permlane16_swap_b32_e32 v149, v164
	v_add_f32_e32 v149, v149, v164
	v_mov_b32_e32 v164, v149
	s_nop 1
	v_permlane32_swap_b32_e32 v149, v164
	v_add_f32_e32 v149, v149, v164
	v_mov_b32_e32 v164, v150
	s_nop 1
	v_permlane16_swap_b32_e32 v150, v164
	v_add_f32_e32 v150, v150, v164
	v_mov_b32_e32 v164, v150
	s_nop 1
	v_permlane32_swap_b32_e32 v150, v164
	v_add_f32_e32 v150, v150, v164
	v_mov_b32_e32 v164, v151
	s_nop 1
	v_permlane16_swap_b32_e32 v151, v164
	v_add_f32_e32 v151, v151, v164
	v_mov_b32_e32 v164, v151
	s_nop 1
	v_permlane32_swap_b32_e32 v151, v164
	v_add_f32_e32 v151, v151, v164
	v_mov_b32_e32 v164, v152
	s_nop 1
	v_permlane16_swap_b32_e32 v152, v164
	v_add_f32_e32 v152, v152, v164
	v_mov_b32_e32 v164, v152
	s_nop 1
	v_permlane32_swap_b32_e32 v152, v164
	v_add_f32_e32 v152, v152, v164
	s_waitcnt vmcnt(0) lgkmcnt(0)
	s_barrier
	ds_read_b128 v[0:3], v247 offset:0
	ds_read_b128 v[4:7], v247 offset:4096
	ds_read_b128 v[8:11], v247 offset:8192
	ds_read_b128 v[12:15], v247 offset:12288
	ds_read_b128 v[16:19], v247 offset:16384
	ds_read_b128 v[20:23], v247 offset:20480
	ds_read_b128 v[24:27], v247 offset:24576
	ds_read_b128 v[28:31], v247 offset:28672
	ds_read_b128 v[32:35], v255 offset:0
	ds_read_b128 v[36:39], v255 offset:4096
	ds_read_b128 v[40:43], v255 offset:8192
	ds_read_b128 v[44:47], v255 offset:12288
	ds_read_b128 v[48:51], v255 offset:16384
	ds_read_b128 v[52:55], v255 offset:20480
	ds_read_b128 v[56:59], v255 offset:24576
	ds_read_b128 v[60:63], v255 offset:28672
	s_cmp_eq_u32 s65, 0
	s_cbranch_scc1 .Lg2_win_rd_lastaQ
	ds_read_b128 v[64:67], v255 offset:32768

.Lg2_win_rd_lastQ:
	s_waitcnt lgkmcnt(0)
	s_barrier
	v_and_b32_e32 v164, 15, v163
	v_lshlrev_b32_e32 v164, 2, v164
	s_mul_i32 s0, s70, 0x440
	v_add_u32_e32 v164, s0, v164
	s_mov_b64 s[2:3], exec
	s_mov_b64 exec, 0xffff
	ds_write_b32 v164, v136 offset:0
	ds_write_b32 v164, v137 offset:64
	ds_write_b32 v164, v138 offset:128
	ds_write_b32 v164, v139 offset:192
	ds_write_b32 v164, v140 offset:256
	ds_write_b32 v164, v141 offset:320
	ds_write_b32 v164, v142 offset:384
	ds_write_b32 v164, v143 offset:448
	ds_write_b32 v164, v144 offset:512
	ds_write_b32 v164, v145 offset:576
	ds_write_b32 v164, v146 offset:640
	ds_write_b32 v164, v147 offset:704
	ds_write_b32 v164, v148 offset:768
	ds_write_b32 v164, v149 offset:832
	ds_write_b32 v164, v150 offset:896
	ds_write_b32 v164, v151 offset:960
	s_cmp_eq_u32 s65, 0
	s_cbranch_scc1 .Lg2_win_sq_wQ
	ds_write_b32 v164, v152 offset:1024
.Lg2_win_sq_wQ:
	s_mov_b64 exec, s[2:3]
	s_waitcnt lgkmcnt(0)
	s_barrier
	v_lshlrev_b32_e32 v165, 2, v163
	ds_read_b32 v166, v165
	ds_read_b32 v167, v165 offset:1088
	ds_read_b32 v168, v165 offset:2176
	ds_read_b32 v169, v165 offset:3264
	s_sub_u32 s0, s38, 28
	s_mul_i32 s0, s0, 0x11000
	s_lshl_b32 s2, s69, 2
	s_add_u32 s0, s0, s2
	s_add_u32 s0, s0, 0x16c00000
	s_add_u32 s0, s26, s0
	s_addc_u32 s1, s27, 0
	s_waitcnt lgkmcnt(0)
	v_add_f32_e32 v166, v166, v167
	v_add_f32_e32 v168, v168, v169
	v_add_f32_e32 v166, v166, v168
	global_store_dword v165, v166, s[0:1]
	s_cmp_eq_u32 s65, 0
	s_cbranch_scc1 .Lg2_win_sq_dQ
	s_mov_b64 s[2:3], exec
	s_mov_b64 exec, 0xffff
	v_cmp_gt_u32_e32 vcc, 16, v163
	s_and_b64 exec, exec, vcc
	s_cbranch_execz .Lg2_win_sq_xQ
	ds_read_b32 v166, v165 offset:1024
	ds_read_b32 v167, v165 offset:2112
	ds_read_b32 v168, v165 offset:3200
	ds_read_b32 v169, v165 offset:4288
	s_waitcnt lgkmcnt(0)
	v_add_f32_e32 v166, v166, v167
	v_add_f32_e32 v168, v168, v169
	v_add_f32_e32 v166, v166, v168
	global_store_dword v165, v166, s[0:1] offset:1024
.Lg2_win_sq_xQ:
	s_mov_b64 exec, s[2:3]
